# GEMM K-loops: swapped s_setprio (load/LDS-DMA segment at priority 1, MFMA segment at 0) on top of the attention priority version
# baseline (speedup 1.0000x reference)
.LBB0_140:
	s_add_u32 s44, s40, 0xfffc0080
	s_addc_u32 s45, s41, -1
	s_add_i32 s51, 0, 0x10000
	s_cmp_eq_u32 s50, 12
	s_cselect_b32 s47, s23, s45
	s_cselect_b32 s46, s35, s44
	s_cselect_b32 s45, s21, s49
	s_cselect_b32 s44, s36, s48
	s_add_i32 s54, 0, 0x14000
	v_add_u32_e32 v140, s51, v185
	v_add_u32_e32 v170, s54, v185
	ds_read_b128 v[128:131], v140
	ds_read_b128 v[132:135], v140 offset:1024
	ds_read_b128 v[136:139], v140 offset:2048
	ds_read_b128 v[140:143], v140 offset:3072
	ds_read_b128 v[144:147], v170
	ds_read_b128 v[148:151], v170 offset:1024
	ds_read_b128 v[166:169], v170 offset:2048
	ds_read_b128 v[170:173], v170 offset:3072
	v_lshl_add_u64 v[182:183], s[40:41], 0, v[160:161]
	s_add_i32 m0, s14, 0xc000
	ds_read_b128 v[174:177], v187
	ds_read_b128 v[178:181], v187 offset:1024
	ds_read_b128 v[188:191], v187 offset:2048
	ds_read_b128 v[192:195], v187 offset:3072
	ds_read_b128 v[204:207], v187 offset:4096
	ds_read_b128 v[208:211], v187 offset:5120
	ds_read_b128 v[212:215], v187 offset:6144
	ds_read_b128 v[216:219], v187 offset:7168
	global_load_lds_dwordx4 v[182:183], off
	v_lshl_add_u64 v[182:183], s[40:41], 0, v[162:163]
	s_add_i32 m0, s14, 0xe000
	s_nop 0
	global_load_lds_dwordx4 v[182:183], off
	s_waitcnt vmcnt(8)
	s_waitcnt lgkmcnt(0)
	s_barrier
	s_setprio 0
	s_waitcnt lgkmcnt(0)
	v_mfma_f32_16x16x32_bf16 v[120:123], v[128:131], v[174:177], v[120:123]
	v_mfma_f32_16x16x32_bf16 v[112:115], v[136:139], v[174:177], v[112:115]
	v_mfma_f32_16x16x32_bf16 v[104:107], v[128:131], v[188:191], v[104:107]
	v_mfma_f32_16x16x32_bf16 v[96:99], v[136:139], v[188:191], v[96:99]
	v_mfma_f32_16x16x32_bf16 v[88:91], v[128:131], v[204:207], v[88:91]
	v_mfma_f32_16x16x32_bf16 v[80:83], v[136:139], v[204:207], v[80:83]
	v_mfma_f32_16x16x32_bf16 v[72:75], v[128:131], v[212:215], v[72:75]
	v_mfma_f32_16x16x32_bf16 v[64:67], v[136:139], v[212:215], v[64:67]
	v_mfma_f32_16x16x32_bf16 v[120:123], v[132:135], v[178:181], v[120:123]
	v_mfma_f32_16x16x32_bf16 v[112:115], v[140:143], v[178:181], v[112:115]
	v_mfma_f32_16x16x32_bf16 v[104:107], v[132:135], v[192:195], v[104:107]
	v_mfma_f32_16x16x32_bf16 v[96:99], v[140:143], v[192:195], v[96:99]
	v_mfma_f32_16x16x32_bf16 v[88:91], v[132:135], v[208:211], v[88:91]
	v_mfma_f32_16x16x32_bf16 v[80:83], v[140:143], v[208:211], v[80:83]
	v_mfma_f32_16x16x32_bf16 v[72:75], v[132:135], v[216:219], v[72:75]
	v_mfma_f32_16x16x32_bf16 v[64:67], v[140:143], v[216:219], v[64:67]
	s_setprio 1
	s_setprio 0
	v_mfma_f32_16x16x32_bf16 v[124:127], v[144:147], v[174:177], v[124:127]
	v_mfma_f32_16x16x32_bf16 v[116:119], v[166:169], v[174:177], v[116:119]
	v_mfma_f32_16x16x32_bf16 v[108:111], v[144:147], v[188:191], v[108:111]
	v_mfma_f32_16x16x32_bf16 v[100:103], v[166:169], v[188:191], v[100:103]
	v_mfma_f32_16x16x32_bf16 v[92:95], v[144:147], v[204:207], v[92:95]
	v_mfma_f32_16x16x32_bf16 v[84:87], v[166:169], v[204:207], v[84:87]
	v_mfma_f32_16x16x32_bf16 v[76:79], v[144:147], v[212:215], v[76:79]
	v_mfma_f32_16x16x32_bf16 v[68:71], v[166:169], v[212:215], v[68:71]
	v_mfma_f32_16x16x32_bf16 v[124:127], v[148:151], v[178:181], v[124:127]
	v_mfma_f32_16x16x32_bf16 v[116:119], v[170:173], v[178:181], v[116:119]
	v_mfma_f32_16x16x32_bf16 v[108:111], v[148:151], v[192:195], v[108:111]
	v_mfma_f32_16x16x32_bf16 v[100:103], v[170:173], v[192:195], v[100:103]
	v_mfma_f32_16x16x32_bf16 v[92:95], v[148:151], v[208:211], v[92:95]
	v_mfma_f32_16x16x32_bf16 v[84:87], v[170:173], v[208:211], v[84:87]
	v_mfma_f32_16x16x32_bf16 v[76:79], v[148:151], v[216:219], v[76:79]
	v_mfma_f32_16x16x32_bf16 v[68:71], v[170:173], v[216:219], v[68:71]
	s_setprio 1
	s_barrier
	s_add_i32 s51, s51, s1
	v_lshl_add_u64 v[182:183], s[44:45], 0, v[196:197]
	s_mov_b32 m0, s51
	ds_read_b128 v[174:177], v187 offset:16384
	ds_read_b128 v[178:181], v187 offset:17408
	ds_read_b128 v[188:191], v187 offset:18432
	ds_read_b128 v[192:195], v187 offset:19456
	ds_read_b128 v[204:207], v187 offset:20480
	ds_read_b128 v[208:211], v187 offset:21504
	ds_read_b128 v[212:215], v187 offset:22528
	ds_read_b128 v[216:219], v187 offset:23552
	global_load_lds_dwordx4 v[182:183], off
	s_add_i32 m0, s51, 0x2000
	s_add_u32 s52, s44, 0x40000
	v_lshl_add_u64 v[220:221], s[44:45], 0, v[152:153]
	s_addc_u32 s53, s45, 0
	s_add_i32 s51, s54, s1
	global_load_lds_dwordx4 v[220:221], off
	v_lshl_add_u64 v[226:227], s[52:53], 0, v[196:197]
	s_mov_b32 m0, s51
	v_lshl_add_u64 v[228:229], s[46:47], 0, v[154:155]
	global_load_lds_dwordx4 v[226:227], off
	v_lshl_add_u64 v[226:227], s[52:53], 0, v[152:153]
	s_add_i32 m0, s51, 0x2000
	s_nop 0
	global_load_lds_dwordx4 v[226:227], off
	v_lshl_add_u64 v[226:227], s[46:47], 0, v[156:157]
	s_mov_b32 m0, s14
	s_nop 0
	global_load_lds_dwordx4 v[226:227], off
	s_mov_b32 m0, s15
	s_nop 0
	global_load_lds_dwordx4 v[228:229], off
	s_waitcnt vmcnt(8)
	s_waitcnt lgkmcnt(0)
	s_barrier
	s_setprio 0
	s_waitcnt lgkmcnt(0)
	v_mfma_f32_16x16x32_bf16 v[56:59], v[128:131], v[174:177], v[56:59]
	v_mfma_f32_16x16x32_bf16 v[48:51], v[136:139], v[174:177], v[48:51]
	v_mfma_f32_16x16x32_bf16 v[40:43], v[128:131], v[188:191], v[40:43]
	v_mfma_f32_16x16x32_bf16 v[32:35], v[136:139], v[188:191], v[32:35]
	v_mfma_f32_16x16x32_bf16 v[24:27], v[128:131], v[204:207], v[24:27]
	v_mfma_f32_16x16x32_bf16 v[16:19], v[136:139], v[204:207], v[16:19]
	v_mfma_f32_16x16x32_bf16 v[8:11], v[128:131], v[212:215], v[8:11]
	v_mfma_f32_16x16x32_bf16 v[0:3], v[136:139], v[212:215], v[0:3]
	v_mfma_f32_16x16x32_bf16 v[56:59], v[132:135], v[178:181], v[56:59]
	v_mfma_f32_16x16x32_bf16 v[48:51], v[140:143], v[178:181], v[48:51]
	v_mfma_f32_16x16x32_bf16 v[40:43], v[132:135], v[192:195], v[40:43]
	v_mfma_f32_16x16x32_bf16 v[32:35], v[140:143], v[192:195], v[32:35]
	v_mfma_f32_16x16x32_bf16 v[24:27], v[132:135], v[208:211], v[24:27]
	v_mfma_f32_16x16x32_bf16 v[16:19], v[140:143], v[208:211], v[16:19]
	v_mfma_f32_16x16x32_bf16 v[8:11], v[132:135], v[216:219], v[8:11]
	v_mfma_f32_16x16x32_bf16 v[0:3], v[140:143], v[216:219], v[0:3]
	s_setprio 1
	s_setprio 0
	v_mfma_f32_16x16x32_bf16 v[60:63], v[144:147], v[174:177], v[60:63]
	v_mfma_f32_16x16x32_bf16 v[52:55], v[166:169], v[174:177], v[52:55]
	v_mfma_f32_16x16x32_bf16 v[44:47], v[144:147], v[188:191], v[44:47]
	v_mfma_f32_16x16x32_bf16 v[36:39], v[166:169], v[188:191], v[36:39]
	v_mfma_f32_16x16x32_bf16 v[28:31], v[144:147], v[204:207], v[28:31]
	v_mfma_f32_16x16x32_bf16 v[20:23], v[166:169], v[204:207], v[20:23]
	v_mfma_f32_16x16x32_bf16 v[12:15], v[144:147], v[212:215], v[12:15]
	v_mfma_f32_16x16x32_bf16 v[4:7], v[166:169], v[212:215], v[4:7]
	v_mfma_f32_16x16x32_bf16 v[60:63], v[148:151], v[178:181], v[60:63]
	v_mfma_f32_16x16x32_bf16 v[52:55], v[170:173], v[178:181], v[52:55]
	v_mfma_f32_16x16x32_bf16 v[44:47], v[148:151], v[192:195], v[44:47]
	v_mfma_f32_16x16x32_bf16 v[36:39], v[170:173], v[192:195], v[36:39]
	v_mfma_f32_16x16x32_bf16 v[28:31], v[148:151], v[208:211], v[28:31]
	v_mfma_f32_16x16x32_bf16 v[20:23], v[170:173], v[208:211], v[20:23]
	v_mfma_f32_16x16x32_bf16 v[12:15], v[148:151], v[216:219], v[12:15]
	v_mfma_f32_16x16x32_bf16 v[4:7], v[170:173], v[216:219], v[4:7]
	s_setprio 1
	s_barrier
	s_add_i32 s51, 0, 0x18000
	s_add_i32 s52, 0, 0x1c000
	v_add_u32_e32 v140, s51, v185
	v_add_u32_e32 v170, s52, v185
	ds_read_b128 v[128:131], v140
	ds_read_b128 v[132:135], v140 offset:1024
	ds_read_b128 v[136:139], v140 offset:2048
	ds_read_b128 v[140:143], v140 offset:3072
	ds_read_b128 v[144:147], v170
	ds_read_b128 v[148:151], v170 offset:1024
	ds_read_b128 v[166:169], v170 offset:2048
	ds_read_b128 v[170:173], v170 offset:3072
	s_add_u32 s46, s46, 0x40000
	s_addc_u32 s47, s47, 0
	s_mov_b32 m0, s17
	v_lshl_add_u64 v[230:231], s[46:47], 0, v[156:157]
	ds_read_b128 v[174:177], v187 offset:32768
	ds_read_b128 v[178:181], v187 offset:33792
	ds_read_b128 v[188:191], v187 offset:34816
	ds_read_b128 v[192:195], v187 offset:35840
	ds_read_b128 v[204:207], v187 offset:36864
	ds_read_b128 v[208:211], v187 offset:37888
	ds_read_b128 v[212:215], v187 offset:38912
	ds_read_b128 v[216:219], v187 offset:39936
	global_load_lds_dwordx4 v[230:231], off
	v_lshl_add_u64 v[230:231], s[46:47], 0, v[154:155]
	s_mov_b32 m0, s26
	s_nop 0
	global_load_lds_dwordx4 v[230:231], off
	s_waitcnt vmcnt(8)
	s_waitcnt lgkmcnt(0)
	s_barrier
	s_setprio 0
	s_waitcnt lgkmcnt(0)
	v_mfma_f32_16x16x32_bf16 v[120:123], v[128:131], v[174:177], v[120:123]
	v_mfma_f32_16x16x32_bf16 v[112:115], v[136:139], v[174:177], v[112:115]
	v_mfma_f32_16x16x32_bf16 v[104:107], v[128:131], v[188:191], v[104:107]
	v_mfma_f32_16x16x32_bf16 v[96:99], v[136:139], v[188:191], v[96:99]
	v_mfma_f32_16x16x32_bf16 v[88:91], v[128:131], v[204:207], v[88:91]
	v_mfma_f32_16x16x32_bf16 v[80:83], v[136:139], v[204:207], v[80:83]
	v_mfma_f32_16x16x32_bf16 v[72:75], v[128:131], v[212:215], v[72:75]
	v_mfma_f32_16x16x32_bf16 v[64:67], v[136:139], v[212:215], v[64:67]
	v_mfma_f32_16x16x32_bf16 v[120:123], v[132:135], v[178:181], v[120:123]
	v_mfma_f32_16x16x32_bf16 v[112:115], v[140:143], v[178:181], v[112:115]
	v_mfma_f32_16x16x32_bf16 v[104:107], v[132:135], v[192:195], v[104:107]
	v_mfma_f32_16x16x32_bf16 v[96:99], v[140:143], v[192:195], v[96:99]
	v_mfma_f32_16x16x32_bf16 v[88:91], v[132:135], v[208:211], v[88:91]
	v_mfma_f32_16x16x32_bf16 v[80:83], v[140:143], v[208:211], v[80:83]
	v_mfma_f32_16x16x32_bf16 v[72:75], v[132:135], v[216:219], v[72:75]
	v_mfma_f32_16x16x32_bf16 v[64:67], v[140:143], v[216:219], v[64:67]
	s_setprio 1
	s_setprio 0
	v_mfma_f32_16x16x32_bf16 v[124:127], v[144:147], v[174:177], v[124:127]
	v_mfma_f32_16x16x32_bf16 v[116:119], v[166:169], v[174:177], v[116:119]
	v_mfma_f32_16x16x32_bf16 v[108:111], v[144:147], v[188:191], v[108:111]
	v_mfma_f32_16x16x32_bf16 v[100:103], v[166:169], v[188:191], v[100:103]
	v_mfma_f32_16x16x32_bf16 v[92:95], v[144:147], v[204:207], v[92:95]
	v_mfma_f32_16x16x32_bf16 v[84:87], v[166:169], v[204:207], v[84:87]
	v_mfma_f32_16x16x32_bf16 v[76:79], v[144:147], v[212:215], v[76:79]
	v_mfma_f32_16x16x32_bf16 v[68:71], v[166:169], v[212:215], v[68:71]
	v_mfma_f32_16x16x32_bf16 v[124:127], v[148:151], v[178:181], v[124:127]
	v_mfma_f32_16x16x32_bf16 v[116:119], v[170:173], v[178:181], v[116:119]
	v_mfma_f32_16x16x32_bf16 v[108:111], v[148:151], v[192:195], v[108:111]
	v_mfma_f32_16x16x32_bf16 v[100:103], v[170:173], v[192:195], v[100:103]
	v_mfma_f32_16x16x32_bf16 v[92:95], v[148:151], v[208:211], v[92:95]
	v_mfma_f32_16x16x32_bf16 v[84:87], v[170:173], v[208:211], v[84:87]
	v_mfma_f32_16x16x32_bf16 v[76:79], v[148:151], v[216:219], v[76:79]
	v_mfma_f32_16x16x32_bf16 v[68:71], v[170:173], v[216:219], v[68:71]
	s_setprio 1
	s_barrier
	s_add_i32 s46, s51, s1
	v_lshl_add_u64 v[182:183], v[182:183], 0, s[88:89]
	s_mov_b32 m0, s46
	ds_read_b128 v[174:177], v187 offset:49152
	ds_read_b128 v[178:181], v187 offset:50176
	ds_read_b128 v[188:191], v187 offset:51200
	ds_read_b128 v[192:195], v187 offset:52224
	ds_read_b128 v[204:207], v187 offset:53248
	ds_read_b128 v[208:211], v187 offset:54272
	ds_read_b128 v[212:215], v187 offset:55296
	ds_read_b128 v[216:219], v187 offset:56320
	global_load_lds_dwordx4 v[182:183], off
	s_add_i32 m0, s46, 0x2000
	s_add_u32 s44, s44, 0x40080
	v_lshl_add_u64 v[182:183], v[220:221], 0, s[88:89]
	s_addc_u32 s45, s45, 0
	s_add_i32 s46, s52, s1
	global_load_lds_dwordx4 v[182:183], off
	v_lshl_add_u64 v[182:183], s[44:45], 0, v[196:197]
	s_mov_b32 m0, s46
	s_nop 0
	global_load_lds_dwordx4 v[182:183], off
	v_lshl_add_u64 v[182:183], s[44:45], 0, v[152:153]
	s_add_i32 m0, s46, 0x2000
	s_nop 0
	global_load_lds_dwordx4 v[182:183], off
	v_lshl_add_u64 v[182:183], v[226:227], 0, s[88:89]
	s_mov_b32 m0, s27
	s_nop 0
	global_load_lds_dwordx4 v[182:183], off
	v_lshl_add_u64 v[182:183], v[228:229], 0, s[88:89]
	s_mov_b32 m0, s28
	s_nop 0
	global_load_lds_dwordx4 v[182:183], off
	s_waitcnt vmcnt(8)
	s_waitcnt lgkmcnt(0)
	s_barrier
	s_setprio 0
	s_waitcnt lgkmcnt(0)
	v_mfma_f32_16x16x32_bf16 v[56:59], v[128:131], v[174:177], v[56:59]
	v_mfma_f32_16x16x32_bf16 v[48:51], v[136:139], v[174:177], v[48:51]
	v_mfma_f32_16x16x32_bf16 v[40:43], v[128:131], v[188:191], v[40:43]
	v_mfma_f32_16x16x32_bf16 v[32:35], v[136:139], v[188:191], v[32:35]
	v_mfma_f32_16x16x32_bf16 v[24:27], v[128:131], v[204:207], v[24:27]
	v_mfma_f32_16x16x32_bf16 v[16:19], v[136:139], v[204:207], v[16:19]
	v_mfma_f32_16x16x32_bf16 v[8:11], v[128:131], v[212:215], v[8:11]
	v_mfma_f32_16x16x32_bf16 v[0:3], v[136:139], v[212:215], v[0:3]
	v_mfma_f32_16x16x32_bf16 v[56:59], v[132:135], v[178:181], v[56:59]
	v_mfma_f32_16x16x32_bf16 v[48:51], v[140:143], v[178:181], v[48:51]
	v_mfma_f32_16x16x32_bf16 v[40:43], v[132:135], v[192:195], v[40:43]
	v_mfma_f32_16x16x32_bf16 v[32:35], v[140:143], v[192:195], v[32:35]
	v_mfma_f32_16x16x32_bf16 v[24:27], v[132:135], v[208:211], v[24:27]
	v_mfma_f32_16x16x32_bf16 v[16:19], v[140:143], v[208:211], v[16:19]
	v_mfma_f32_16x16x32_bf16 v[8:11], v[132:135], v[216:219], v[8:11]
	v_mfma_f32_16x16x32_bf16 v[0:3], v[140:143], v[216:219], v[0:3]
	s_setprio 1
	s_setprio 0
	v_mfma_f32_16x16x32_bf16 v[60:63], v[144:147], v[174:177], v[60:63]
	v_mfma_f32_16x16x32_bf16 v[52:55], v[166:169], v[174:177], v[52:55]
	v_mfma_f32_16x16x32_bf16 v[44:47], v[144:147], v[188:191], v[44:47]
	v_mfma_f32_16x16x32_bf16 v[36:39], v[166:169], v[188:191], v[36:39]
	v_mfma_f32_16x16x32_bf16 v[28:31], v[144:147], v[204:207], v[28:31]
	v_mfma_f32_16x16x32_bf16 v[20:23], v[166:169], v[204:207], v[20:23]
	v_mfma_f32_16x16x32_bf16 v[12:15], v[144:147], v[212:215], v[12:15]
	v_mfma_f32_16x16x32_bf16 v[4:7], v[166:169], v[212:215], v[4:7]
	v_mfma_f32_16x16x32_bf16 v[60:63], v[148:151], v[178:181], v[60:63]
	v_mfma_f32_16x16x32_bf16 v[52:55], v[170:173], v[178:181], v[52:55]
	v_mfma_f32_16x16x32_bf16 v[44:47], v[148:151], v[192:195], v[44:47]
	v_mfma_f32_16x16x32_bf16 v[36:39], v[170:173], v[192:195], v[36:39]
	v_mfma_f32_16x16x32_bf16 v[28:31], v[148:151], v[208:211], v[28:31]
	v_mfma_f32_16x16x32_bf16 v[20:23], v[170:173], v[208:211], v[20:23]
	v_mfma_f32_16x16x32_bf16 v[12:15], v[148:151], v[216:219], v[12:15]
	v_mfma_f32_16x16x32_bf16 v[4:7], v[170:173], v[216:219], v[4:7]
	s_setprio 1
	s_barrier
	s_add_i32 s50, s50, 2
	s_add_u32 s40, s40, 0x100
	s_addc_u32 s41, s41, 0
	s_add_u32 s48, s48, 0x100
	s_addc_u32 s49, s49, 0
	s_cmp_gt_u32 s50, 13
	s_cbranch_scc0 .LBB0_140
	s_setprio 0
	s_and_b64 vcc, exec, s[18:19]
	s_cbranch_vccz .LBB0_143
	s_barrier

.LBB0_416:
	s_add_i32 s56, s52, 2
	s_add_u32 s57, s50, 0x80
	s_addc_u32 s53, s51, 0
	s_add_i32 s63, 0, 0x10000
	s_cmp_eq_u32 s99, s52
	s_cselect_b32 s53, s9, s53
	s_cselect_b32 s52, s8, s57
	s_cselect_b32 s61, s85, s55
	s_cselect_b32 s60, s84, s54
	s_add_i32 s57, 0, 0x14000
	v_add_u32_e32 v140, s63, v195
	v_add_u32_e32 v152, s57, v195
	ds_read_b128 v[128:131], v140
	ds_read_b128 v[132:135], v140 offset:1024
	ds_read_b128 v[136:139], v140 offset:2048
	ds_read_b128 v[140:143], v140 offset:3072
	ds_read_b128 v[144:147], v152
	ds_read_b128 v[148:151], v152 offset:1024
	ds_read_b128 v[172:175], v152 offset:2048
	ds_read_b128 v[176:179], v152 offset:3072
	v_lshl_add_u64 v[152:153], s[50:51], 0, v[168:169]
	s_add_i32 m0, s15, 0xc000
	ds_read_b128 v[180:183], v205
	ds_read_b128 v[184:187], v205 offset:1024
	ds_read_b128 v[188:191], v205 offset:2048
	ds_read_b128 v[206:209], v205 offset:3072
	ds_read_b128 v[210:213], v205 offset:4096
	ds_read_b128 v[214:217], v205 offset:5120
	ds_read_b128 v[218:221], v205 offset:6144
	ds_read_b128 v[226:229], v205 offset:7168
	global_load_lds_dwordx4 v[152:153], off
	v_lshl_add_u64 v[152:153], s[50:51], 0, v[170:171]
	s_add_i32 m0, s15, 0xe000
	s_nop 0
	global_load_lds_dwordx4 v[152:153], off
	s_waitcnt vmcnt(8)
	s_waitcnt lgkmcnt(0)
	s_barrier
	s_setprio 0
	s_waitcnt lgkmcnt(0)
	v_mfma_f32_16x16x32_bf16 v[124:127], v[128:131], v[180:183], v[124:127]
	v_mfma_f32_16x16x32_bf16 v[120:123], v[136:139], v[180:183], v[120:123]
	v_mfma_f32_16x16x32_bf16 v[116:119], v[128:131], v[188:191], v[116:119]
	v_mfma_f32_16x16x32_bf16 v[112:115], v[136:139], v[188:191], v[112:115]
	v_mfma_f32_16x16x32_bf16 v[108:111], v[128:131], v[210:213], v[108:111]
	v_mfma_f32_16x16x32_bf16 v[104:107], v[136:139], v[210:213], v[104:107]
	v_mfma_f32_16x16x32_bf16 v[100:103], v[128:131], v[218:221], v[100:103]
	v_mfma_f32_16x16x32_bf16 v[96:99], v[136:139], v[218:221], v[96:99]
	v_mfma_f32_16x16x32_bf16 v[124:127], v[132:135], v[184:187], v[124:127]
	v_mfma_f32_16x16x32_bf16 v[120:123], v[140:143], v[184:187], v[120:123]
	v_mfma_f32_16x16x32_bf16 v[116:119], v[132:135], v[206:209], v[116:119]
	v_mfma_f32_16x16x32_bf16 v[112:115], v[140:143], v[206:209], v[112:115]
	v_mfma_f32_16x16x32_bf16 v[108:111], v[132:135], v[214:217], v[108:111]
	v_mfma_f32_16x16x32_bf16 v[104:107], v[140:143], v[214:217], v[104:107]
	v_mfma_f32_16x16x32_bf16 v[100:103], v[132:135], v[226:229], v[100:103]
	v_mfma_f32_16x16x32_bf16 v[96:99], v[140:143], v[226:229], v[96:99]
	s_setprio 1
	s_setprio 0
	v_mfma_f32_16x16x32_bf16 v[60:63], v[144:147], v[180:183], v[60:63]
	v_mfma_f32_16x16x32_bf16 v[56:59], v[172:175], v[180:183], v[56:59]
	v_mfma_f32_16x16x32_bf16 v[52:55], v[144:147], v[188:191], v[52:55]
	v_mfma_f32_16x16x32_bf16 v[48:51], v[172:175], v[188:191], v[48:51]
	v_mfma_f32_16x16x32_bf16 v[44:47], v[144:147], v[210:213], v[44:47]
	v_mfma_f32_16x16x32_bf16 v[40:43], v[172:175], v[210:213], v[40:43]
	v_mfma_f32_16x16x32_bf16 v[36:39], v[144:147], v[218:221], v[36:39]
	v_mfma_f32_16x16x32_bf16 v[32:35], v[172:175], v[218:221], v[32:35]
	v_mfma_f32_16x16x32_bf16 v[60:63], v[148:151], v[184:187], v[60:63]
	v_mfma_f32_16x16x32_bf16 v[56:59], v[176:179], v[184:187], v[56:59]
	v_mfma_f32_16x16x32_bf16 v[52:55], v[148:151], v[206:209], v[52:55]
	v_mfma_f32_16x16x32_bf16 v[48:51], v[176:179], v[206:209], v[48:51]
	v_mfma_f32_16x16x32_bf16 v[44:47], v[148:151], v[214:217], v[44:47]
	v_mfma_f32_16x16x32_bf16 v[40:43], v[176:179], v[214:217], v[40:43]
	v_mfma_f32_16x16x32_bf16 v[36:39], v[148:151], v[226:229], v[36:39]
	v_mfma_f32_16x16x32_bf16 v[32:35], v[176:179], v[226:229], v[32:35]
	s_setprio 1
	s_barrier
	s_add_i32 s63, s63, s14
	v_lshl_add_u64 v[152:153], s[60:61], 0, v[156:157]
	s_mov_b32 m0, s63
	ds_read_b128 v[180:183], v205 offset:16384
	ds_read_b128 v[184:187], v205 offset:17408
	ds_read_b128 v[188:191], v205 offset:18432
	ds_read_b128 v[206:209], v205 offset:19456
	ds_read_b128 v[210:213], v205 offset:20480
	ds_read_b128 v[214:217], v205 offset:21504
	ds_read_b128 v[218:221], v205 offset:22528
	ds_read_b128 v[226:229], v205 offset:23552
	global_load_lds_dwordx4 v[152:153], off
	s_add_i32 m0, s63, 0x2000
	v_lshl_add_u64 v[192:193], s[60:61], 0, v[160:161]
	s_add_u32 s60, s60, s23
	s_addc_u32 s61, s61, 0
	s_add_i32 s57, s57, s14
	global_load_lds_dwordx4 v[192:193], off
	v_lshl_add_u64 v[230:231], s[60:61], 0, v[156:157]
	s_mov_b32 m0, s57
	v_lshl_add_u64 v[232:233], s[60:61], 0, v[160:161]
	global_load_lds_dwordx4 v[230:231], off
	s_add_i32 m0, s57, 0x2000
	v_lshl_add_u64 v[234:235], s[52:53], 0, v[154:155]
	global_load_lds_dwordx4 v[232:233], off
	s_mov_b32 m0, s15
	v_lshl_add_u64 v[236:237], s[52:53], 0, v[158:159]
	global_load_lds_dwordx4 v[234:235], off
	s_mov_b32 m0, s59
	s_nop 0
	global_load_lds_dwordx4 v[236:237], off
	s_waitcnt vmcnt(8)
	s_waitcnt lgkmcnt(0)
	s_barrier
	s_setprio 0
	s_waitcnt lgkmcnt(0)
	v_mfma_f32_16x16x32_bf16 v[92:95], v[128:131], v[180:183], v[92:95]
	v_mfma_f32_16x16x32_bf16 v[88:91], v[136:139], v[180:183], v[88:91]
	v_mfma_f32_16x16x32_bf16 v[84:87], v[128:131], v[188:191], v[84:87]
	v_mfma_f32_16x16x32_bf16 v[80:83], v[136:139], v[188:191], v[80:83]
	v_mfma_f32_16x16x32_bf16 v[76:79], v[128:131], v[210:213], v[76:79]
	v_mfma_f32_16x16x32_bf16 v[72:75], v[136:139], v[210:213], v[72:75]
	v_mfma_f32_16x16x32_bf16 v[68:71], v[128:131], v[218:221], v[68:71]
	v_mfma_f32_16x16x32_bf16 v[64:67], v[136:139], v[218:221], v[64:67]
	v_mfma_f32_16x16x32_bf16 v[92:95], v[132:135], v[184:187], v[92:95]
	v_mfma_f32_16x16x32_bf16 v[88:91], v[140:143], v[184:187], v[88:91]
	v_mfma_f32_16x16x32_bf16 v[84:87], v[132:135], v[206:209], v[84:87]
	v_mfma_f32_16x16x32_bf16 v[80:83], v[140:143], v[206:209], v[80:83]
	v_mfma_f32_16x16x32_bf16 v[76:79], v[132:135], v[214:217], v[76:79]
	v_mfma_f32_16x16x32_bf16 v[72:75], v[140:143], v[214:217], v[72:75]
	v_mfma_f32_16x16x32_bf16 v[68:71], v[132:135], v[226:229], v[68:71]
	v_mfma_f32_16x16x32_bf16 v[64:67], v[140:143], v[226:229], v[64:67]
	s_setprio 1
	s_setprio 0
	v_mfma_f32_16x16x32_bf16 v[28:31], v[144:147], v[180:183], v[28:31]
	v_mfma_f32_16x16x32_bf16 v[24:27], v[172:175], v[180:183], v[24:27]
	v_mfma_f32_16x16x32_bf16 v[20:23], v[144:147], v[188:191], v[20:23]
	v_mfma_f32_16x16x32_bf16 v[16:19], v[172:175], v[188:191], v[16:19]
	v_mfma_f32_16x16x32_bf16 v[12:15], v[144:147], v[210:213], v[12:15]
	v_mfma_f32_16x16x32_bf16 v[8:11], v[172:175], v[210:213], v[8:11]
	v_mfma_f32_16x16x32_bf16 v[4:7], v[144:147], v[218:221], v[4:7]
	v_mfma_f32_16x16x32_bf16 v[0:3], v[172:175], v[218:221], v[0:3]
	v_mfma_f32_16x16x32_bf16 v[28:31], v[148:151], v[184:187], v[28:31]
	v_mfma_f32_16x16x32_bf16 v[24:27], v[176:179], v[184:187], v[24:27]
	v_mfma_f32_16x16x32_bf16 v[20:23], v[148:151], v[206:209], v[20:23]
	v_mfma_f32_16x16x32_bf16 v[16:19], v[176:179], v[206:209], v[16:19]
	v_mfma_f32_16x16x32_bf16 v[12:15], v[148:151], v[214:217], v[12:15]
	v_mfma_f32_16x16x32_bf16 v[8:11], v[176:179], v[214:217], v[8:11]
	v_mfma_f32_16x16x32_bf16 v[4:7], v[148:151], v[226:229], v[4:7]
	v_mfma_f32_16x16x32_bf16 v[0:3], v[176:179], v[226:229], v[0:3]
	s_setprio 1
	s_barrier
	s_add_i32 s57, 0, 0x18000
	s_add_i32 s60, 0, 0x1c000
	v_add_u32_e32 v140, s57, v195
	v_add_u32_e32 v176, s60, v195
	ds_read_b128 v[128:131], v140
	ds_read_b128 v[132:135], v140 offset:1024
	ds_read_b128 v[136:139], v140 offset:2048
	ds_read_b128 v[140:143], v140 offset:3072
	ds_read_b128 v[144:147], v176
	ds_read_b128 v[148:151], v176 offset:1024
	ds_read_b128 v[172:175], v176 offset:2048
	ds_read_b128 v[176:179], v176 offset:3072
	s_add_u32 s52, s52, s12
	s_addc_u32 s53, s53, 0
	s_mov_b32 m0, s28
	v_lshl_add_u64 v[238:239], s[52:53], 0, v[154:155]
	ds_read_b128 v[180:183], v205 offset:32768
	ds_read_b128 v[184:187], v205 offset:33792
	ds_read_b128 v[188:191], v205 offset:34816
	ds_read_b128 v[206:209], v205 offset:35840
	ds_read_b128 v[210:213], v205 offset:36864
	ds_read_b128 v[214:217], v205 offset:37888
	ds_read_b128 v[218:221], v205 offset:38912
	ds_read_b128 v[226:229], v205 offset:39936
	global_load_lds_dwordx4 v[238:239], off
	v_lshl_add_u64 v[238:239], s[52:53], 0, v[158:159]
	s_mov_b32 m0, s29
	s_nop 0
	global_load_lds_dwordx4 v[238:239], off
	s_waitcnt vmcnt(8)
	s_waitcnt lgkmcnt(0)
	s_barrier
	s_setprio 0
	s_waitcnt lgkmcnt(0)
	v_mfma_f32_16x16x32_bf16 v[124:127], v[128:131], v[180:183], v[124:127]
	v_mfma_f32_16x16x32_bf16 v[120:123], v[136:139], v[180:183], v[120:123]
	v_mfma_f32_16x16x32_bf16 v[116:119], v[128:131], v[188:191], v[116:119]
	v_mfma_f32_16x16x32_bf16 v[112:115], v[136:139], v[188:191], v[112:115]
	v_mfma_f32_16x16x32_bf16 v[108:111], v[128:131], v[210:213], v[108:111]
	v_mfma_f32_16x16x32_bf16 v[104:107], v[136:139], v[210:213], v[104:107]
	v_mfma_f32_16x16x32_bf16 v[100:103], v[128:131], v[218:221], v[100:103]
	v_mfma_f32_16x16x32_bf16 v[96:99], v[136:139], v[218:221], v[96:99]
	v_mfma_f32_16x16x32_bf16 v[124:127], v[132:135], v[184:187], v[124:127]
	v_mfma_f32_16x16x32_bf16 v[120:123], v[140:143], v[184:187], v[120:123]
	v_mfma_f32_16x16x32_bf16 v[116:119], v[132:135], v[206:209], v[116:119]
	v_mfma_f32_16x16x32_bf16 v[112:115], v[140:143], v[206:209], v[112:115]
	v_mfma_f32_16x16x32_bf16 v[108:111], v[132:135], v[214:217], v[108:111]
	v_mfma_f32_16x16x32_bf16 v[104:107], v[140:143], v[214:217], v[104:107]
	v_mfma_f32_16x16x32_bf16 v[100:103], v[132:135], v[226:229], v[100:103]
	v_mfma_f32_16x16x32_bf16 v[96:99], v[140:143], v[226:229], v[96:99]
	s_setprio 1
	s_setprio 0
	v_mfma_f32_16x16x32_bf16 v[60:63], v[144:147], v[180:183], v[60:63]
	v_mfma_f32_16x16x32_bf16 v[56:59], v[172:175], v[180:183], v[56:59]
	v_mfma_f32_16x16x32_bf16 v[52:55], v[144:147], v[188:191], v[52:55]
	v_mfma_f32_16x16x32_bf16 v[48:51], v[172:175], v[188:191], v[48:51]
	v_mfma_f32_16x16x32_bf16 v[44:47], v[144:147], v[210:213], v[44:47]
	v_mfma_f32_16x16x32_bf16 v[40:43], v[172:175], v[210:213], v[40:43]
	v_mfma_f32_16x16x32_bf16 v[36:39], v[144:147], v[218:221], v[36:39]
	v_mfma_f32_16x16x32_bf16 v[32:35], v[172:175], v[218:221], v[32:35]
	v_mfma_f32_16x16x32_bf16 v[60:63], v[148:151], v[184:187], v[60:63]
	v_mfma_f32_16x16x32_bf16 v[56:59], v[176:179], v[184:187], v[56:59]
	v_mfma_f32_16x16x32_bf16 v[52:55], v[148:151], v[206:209], v[52:55]
	v_mfma_f32_16x16x32_bf16 v[48:51], v[176:179], v[206:209], v[48:51]
	v_mfma_f32_16x16x32_bf16 v[44:47], v[148:151], v[214:217], v[44:47]
	v_mfma_f32_16x16x32_bf16 v[40:43], v[176:179], v[214:217], v[40:43]
	v_mfma_f32_16x16x32_bf16 v[36:39], v[148:151], v[226:229], v[36:39]
	v_mfma_f32_16x16x32_bf16 v[32:35], v[176:179], v[226:229], v[32:35]
	s_setprio 1
	s_barrier
	s_add_i32 s52, s57, s14
	v_lshl_add_u64 v[152:153], v[152:153], 0, s[88:89]
	s_mov_b32 m0, s52
	ds_read_b128 v[180:183], v205 offset:49152
	ds_read_b128 v[184:187], v205 offset:50176
	ds_read_b128 v[188:191], v205 offset:51200
	ds_read_b128 v[206:209], v205 offset:52224
	ds_read_b128 v[210:213], v205 offset:53248
	ds_read_b128 v[214:217], v205 offset:54272
	ds_read_b128 v[218:221], v205 offset:55296
	ds_read_b128 v[226:229], v205 offset:56320
	global_load_lds_dwordx4 v[152:153], off
	v_lshl_add_u64 v[152:153], v[192:193], 0, s[88:89]
	s_add_i32 m0, s52, 0x2000
	s_add_i32 s52, s60, s14
	global_load_lds_dwordx4 v[152:153], off
	v_lshl_add_u64 v[152:153], v[230:231], 0, s[88:89]
	s_mov_b32 m0, s52
	s_nop 0
	global_load_lds_dwordx4 v[152:153], off
	v_lshl_add_u64 v[152:153], v[232:233], 0, s[88:89]
	s_add_i32 m0, s52, 0x2000
	s_nop 0
	global_load_lds_dwordx4 v[152:153], off
	v_lshl_add_u64 v[152:153], v[234:235], 0, s[88:89]
	s_mov_b32 m0, s26
	s_nop 0
	global_load_lds_dwordx4 v[152:153], off
	v_lshl_add_u64 v[152:153], v[236:237], 0, s[88:89]
	s_mov_b32 m0, s27
	s_nop 0
	global_load_lds_dwordx4 v[152:153], off
	s_waitcnt vmcnt(8)
	s_waitcnt lgkmcnt(0)
	s_barrier
	s_setprio 0
	s_waitcnt lgkmcnt(0)
	v_mfma_f32_16x16x32_bf16 v[92:95], v[128:131], v[180:183], v[92:95]
	v_mfma_f32_16x16x32_bf16 v[88:91], v[136:139], v[180:183], v[88:91]
	v_mfma_f32_16x16x32_bf16 v[84:87], v[128:131], v[188:191], v[84:87]
	v_mfma_f32_16x16x32_bf16 v[80:83], v[136:139], v[188:191], v[80:83]
	v_mfma_f32_16x16x32_bf16 v[76:79], v[128:131], v[210:213], v[76:79]
	v_mfma_f32_16x16x32_bf16 v[72:75], v[136:139], v[210:213], v[72:75]
	v_mfma_f32_16x16x32_bf16 v[68:71], v[128:131], v[218:221], v[68:71]
	v_mfma_f32_16x16x32_bf16 v[64:67], v[136:139], v[218:221], v[64:67]
	v_mfma_f32_16x16x32_bf16 v[92:95], v[132:135], v[184:187], v[92:95]
	v_mfma_f32_16x16x32_bf16 v[88:91], v[140:143], v[184:187], v[88:91]
	v_mfma_f32_16x16x32_bf16 v[84:87], v[132:135], v[206:209], v[84:87]
	v_mfma_f32_16x16x32_bf16 v[80:83], v[140:143], v[206:209], v[80:83]
	v_mfma_f32_16x16x32_bf16 v[76:79], v[132:135], v[214:217], v[76:79]
	v_mfma_f32_16x16x32_bf16 v[72:75], v[140:143], v[214:217], v[72:75]
	v_mfma_f32_16x16x32_bf16 v[68:71], v[132:135], v[226:229], v[68:71]
	v_mfma_f32_16x16x32_bf16 v[64:67], v[140:143], v[226:229], v[64:67]
	s_setprio 1
	s_setprio 0
	v_mfma_f32_16x16x32_bf16 v[28:31], v[144:147], v[180:183], v[28:31]
	v_mfma_f32_16x16x32_bf16 v[24:27], v[172:175], v[180:183], v[24:27]
	v_mfma_f32_16x16x32_bf16 v[20:23], v[144:147], v[188:191], v[20:23]
	v_mfma_f32_16x16x32_bf16 v[16:19], v[172:175], v[188:191], v[16:19]
	v_mfma_f32_16x16x32_bf16 v[12:15], v[144:147], v[210:213], v[12:15]
	v_mfma_f32_16x16x32_bf16 v[8:11], v[172:175], v[210:213], v[8:11]
	v_mfma_f32_16x16x32_bf16 v[4:7], v[144:147], v[218:221], v[4:7]
	v_mfma_f32_16x16x32_bf16 v[0:3], v[172:175], v[218:221], v[0:3]
	v_mfma_f32_16x16x32_bf16 v[28:31], v[148:151], v[184:187], v[28:31]
	v_mfma_f32_16x16x32_bf16 v[24:27], v[176:179], v[184:187], v[24:27]
	v_mfma_f32_16x16x32_bf16 v[20:23], v[148:151], v[206:209], v[20:23]
	v_mfma_f32_16x16x32_bf16 v[16:19], v[176:179], v[206:209], v[16:19]
	v_mfma_f32_16x16x32_bf16 v[12:15], v[148:151], v[214:217], v[12:15]
	v_mfma_f32_16x16x32_bf16 v[8:11], v[176:179], v[214:217], v[8:11]
	v_mfma_f32_16x16x32_bf16 v[4:7], v[148:151], v[226:229], v[4:7]
	v_mfma_f32_16x16x32_bf16 v[0:3], v[176:179], v[226:229], v[0:3]
	s_setprio 1
	s_barrier
	s_add_u32 s50, s50, 0x100
	s_addc_u32 s51, s51, 0
	s_add_u32 s54, s54, 0x100
	s_addc_u32 s55, s55, 0
	s_cmp_ge_u32 s56, s91
	s_mov_b32 s52, s56
	s_cbranch_scc0 .LBB0_416
	s_setprio 0
	s_and_b64 vcc, exec, s[80:81]
	s_cbranch_vccz .LBB0_419
	s_barrier

.LBB0_855:
	s_add_i32 s52, s44, 2
	s_add_u32 s53, s34, 0x80
	s_addc_u32 s45, s35, 0
	s_add_i32 s56, 0, 0x10000
	s_cmp_eq_u32 s48, s44
	s_cselect_b32 s45, s25, s45
	s_cselect_b32 s44, s24, s53
	v_add_u32_e32 v142, s56, v145
	s_cselect_b32 s55, s31, s47
	s_cselect_b32 s54, s30, s46
	s_add_i32 s53, 0, 0x14000
	ds_read_b128 v[138:141], v142
	ds_read_b128 v[148:151], v142 offset:1024
	ds_read_b128 v[152:155], v142 offset:2048
	ds_read_b128 v[156:159], v142 offset:3072
	v_add_u32_e32 v142, s53, v145
	ds_read_b128 v[160:163], v142
	ds_read_b128 v[164:167], v142 offset:1024
	ds_read_b128 v[168:171], v142 offset:2048
	ds_read_b128 v[172:175], v142 offset:3072
	v_lshl_add_u64 v[142:143], s[34:35], 0, v[134:135]
	s_add_i32 m0, s14, 0xc000
	ds_read_b128 v[176:179], v147
	ds_read_b128 v[180:183], v147 offset:1024
	ds_read_b128 v[184:187], v147 offset:2048
	ds_read_b128 v[188:191], v147 offset:3072
	ds_read_b128 v[192:195], v147 offset:4096
	ds_read_b128 v[204:207], v147 offset:5120
	ds_read_b128 v[208:211], v147 offset:6144
	ds_read_b128 v[212:215], v147 offset:7168
	global_load_lds_dwordx4 v[142:143], off
	v_lshl_add_u64 v[142:143], s[34:35], 0, v[136:137]
	s_add_i32 m0, s14, 0xe000
	s_nop 0
	global_load_lds_dwordx4 v[142:143], off
	s_waitcnt vmcnt(8)
	s_waitcnt lgkmcnt(0)
	s_barrier
	s_setprio 0
	s_waitcnt lgkmcnt(0)
	v_mfma_f32_16x16x32_bf16 v[124:127], v[138:141], v[176:179], v[124:127]
	v_mfma_f32_16x16x32_bf16 v[120:123], v[152:155], v[176:179], v[120:123]
	v_mfma_f32_16x16x32_bf16 v[108:111], v[138:141], v[184:187], v[108:111]
	v_mfma_f32_16x16x32_bf16 v[104:107], v[152:155], v[184:187], v[104:107]
	v_mfma_f32_16x16x32_bf16 v[92:95], v[138:141], v[192:195], v[92:95]
	v_mfma_f32_16x16x32_bf16 v[88:91], v[152:155], v[192:195], v[88:91]
	v_mfma_f32_16x16x32_bf16 v[76:79], v[138:141], v[208:211], v[76:79]
	v_mfma_f32_16x16x32_bf16 v[72:75], v[152:155], v[208:211], v[72:75]
	v_mfma_f32_16x16x32_bf16 v[124:127], v[148:151], v[180:183], v[124:127]
	v_mfma_f32_16x16x32_bf16 v[120:123], v[156:159], v[180:183], v[120:123]
	v_mfma_f32_16x16x32_bf16 v[108:111], v[148:151], v[188:191], v[108:111]
	v_mfma_f32_16x16x32_bf16 v[104:107], v[156:159], v[188:191], v[104:107]
	v_mfma_f32_16x16x32_bf16 v[92:95], v[148:151], v[204:207], v[92:95]
	v_mfma_f32_16x16x32_bf16 v[88:91], v[156:159], v[204:207], v[88:91]
	v_mfma_f32_16x16x32_bf16 v[76:79], v[148:151], v[212:215], v[76:79]
	v_mfma_f32_16x16x32_bf16 v[72:75], v[156:159], v[212:215], v[72:75]
	s_setprio 1
	s_setprio 0
	v_mfma_f32_16x16x32_bf16 v[116:119], v[160:163], v[176:179], v[116:119]
	v_mfma_f32_16x16x32_bf16 v[112:115], v[168:171], v[176:179], v[112:115]
	v_mfma_f32_16x16x32_bf16 v[100:103], v[160:163], v[184:187], v[100:103]
	v_mfma_f32_16x16x32_bf16 v[96:99], v[168:171], v[184:187], v[96:99]
	v_mfma_f32_16x16x32_bf16 v[84:87], v[160:163], v[192:195], v[84:87]
	v_mfma_f32_16x16x32_bf16 v[80:83], v[168:171], v[192:195], v[80:83]
	v_mfma_f32_16x16x32_bf16 v[68:71], v[160:163], v[208:211], v[68:71]
	v_mfma_f32_16x16x32_bf16 v[64:67], v[168:171], v[208:211], v[64:67]
	v_mfma_f32_16x16x32_bf16 v[116:119], v[164:167], v[180:183], v[116:119]
	v_mfma_f32_16x16x32_bf16 v[112:115], v[172:175], v[180:183], v[112:115]
	v_mfma_f32_16x16x32_bf16 v[100:103], v[164:167], v[188:191], v[100:103]
	v_mfma_f32_16x16x32_bf16 v[96:99], v[172:175], v[188:191], v[96:99]
	v_mfma_f32_16x16x32_bf16 v[84:87], v[164:167], v[204:207], v[84:87]
	v_mfma_f32_16x16x32_bf16 v[80:83], v[172:175], v[204:207], v[80:83]
	v_mfma_f32_16x16x32_bf16 v[68:71], v[164:167], v[212:215], v[68:71]
	v_mfma_f32_16x16x32_bf16 v[64:67], v[172:175], v[212:215], v[64:67]
	s_setprio 1
	s_barrier
	s_add_i32 s56, s56, s11
	v_lshl_add_u64 v[142:143], s[54:55], 0, v[196:197]
	s_mov_b32 m0, s56
	ds_read_b128 v[176:179], v147 offset:16384
	ds_read_b128 v[180:183], v147 offset:17408
	ds_read_b128 v[184:187], v147 offset:18432
	ds_read_b128 v[188:191], v147 offset:19456
	ds_read_b128 v[192:195], v147 offset:20480
	ds_read_b128 v[204:207], v147 offset:21504
	ds_read_b128 v[208:211], v147 offset:22528
	ds_read_b128 v[212:215], v147 offset:23552
	global_load_lds_dwordx4 v[142:143], off
	s_add_i32 m0, s56, 0x2000
	v_lshl_add_u64 v[216:217], s[54:55], 0, v[128:129]
	s_add_u32 s54, s54, s12
	s_addc_u32 s55, s55, 0
	s_add_i32 s53, s53, s11
	global_load_lds_dwordx4 v[216:217], off
	v_lshl_add_u64 v[218:219], s[54:55], 0, v[196:197]
	s_mov_b32 m0, s53
	v_lshl_add_u64 v[220:221], s[54:55], 0, v[128:129]
	global_load_lds_dwordx4 v[218:219], off
	s_add_i32 m0, s53, 0x2000
	v_lshl_add_u64 v[226:227], s[44:45], 0, v[132:133]
	global_load_lds_dwordx4 v[220:221], off
	s_mov_b32 m0, s14
	v_lshl_add_u64 v[228:229], s[44:45], 0, v[130:131]
	global_load_lds_dwordx4 v[226:227], off
	s_mov_b32 m0, s15
	s_nop 0
	global_load_lds_dwordx4 v[228:229], off
	s_waitcnt vmcnt(8)
	s_waitcnt lgkmcnt(0)
	s_barrier
	s_setprio 0
	s_waitcnt lgkmcnt(0)
	v_mfma_f32_16x16x32_bf16 v[60:63], v[138:141], v[176:179], v[60:63]
	v_mfma_f32_16x16x32_bf16 v[56:59], v[152:155], v[176:179], v[56:59]
	v_mfma_f32_16x16x32_bf16 v[44:47], v[138:141], v[184:187], v[44:47]
	v_mfma_f32_16x16x32_bf16 v[40:43], v[152:155], v[184:187], v[40:43]
	v_mfma_f32_16x16x32_bf16 v[28:31], v[138:141], v[192:195], v[28:31]
	v_mfma_f32_16x16x32_bf16 v[24:27], v[152:155], v[192:195], v[24:27]
	v_mfma_f32_16x16x32_bf16 v[12:15], v[138:141], v[208:211], v[12:15]
	v_mfma_f32_16x16x32_bf16 v[8:11], v[152:155], v[208:211], v[8:11]
	v_mfma_f32_16x16x32_bf16 v[60:63], v[148:151], v[180:183], v[60:63]
	v_mfma_f32_16x16x32_bf16 v[56:59], v[156:159], v[180:183], v[56:59]
	v_mfma_f32_16x16x32_bf16 v[44:47], v[148:151], v[188:191], v[44:47]
	v_mfma_f32_16x16x32_bf16 v[40:43], v[156:159], v[188:191], v[40:43]
	v_mfma_f32_16x16x32_bf16 v[28:31], v[148:151], v[204:207], v[28:31]
	v_mfma_f32_16x16x32_bf16 v[24:27], v[156:159], v[204:207], v[24:27]
	v_mfma_f32_16x16x32_bf16 v[12:15], v[148:151], v[212:215], v[12:15]
	v_mfma_f32_16x16x32_bf16 v[8:11], v[156:159], v[212:215], v[8:11]
	s_setprio 1
	s_setprio 0
	v_mfma_f32_16x16x32_bf16 v[52:55], v[160:163], v[176:179], v[52:55]
	v_mfma_f32_16x16x32_bf16 v[48:51], v[168:171], v[176:179], v[48:51]
	v_mfma_f32_16x16x32_bf16 v[36:39], v[160:163], v[184:187], v[36:39]
	v_mfma_f32_16x16x32_bf16 v[32:35], v[168:171], v[184:187], v[32:35]
	v_mfma_f32_16x16x32_bf16 v[20:23], v[160:163], v[192:195], v[20:23]
	v_mfma_f32_16x16x32_bf16 v[16:19], v[168:171], v[192:195], v[16:19]
	v_mfma_f32_16x16x32_bf16 v[4:7], v[160:163], v[208:211], v[4:7]
	v_mfma_f32_16x16x32_bf16 v[0:3], v[168:171], v[208:211], v[0:3]
	v_mfma_f32_16x16x32_bf16 v[52:55], v[164:167], v[180:183], v[52:55]
	v_mfma_f32_16x16x32_bf16 v[48:51], v[172:175], v[180:183], v[48:51]
	v_mfma_f32_16x16x32_bf16 v[36:39], v[164:167], v[188:191], v[36:39]
	v_mfma_f32_16x16x32_bf16 v[32:35], v[172:175], v[188:191], v[32:35]
	v_mfma_f32_16x16x32_bf16 v[20:23], v[164:167], v[204:207], v[20:23]
	v_mfma_f32_16x16x32_bf16 v[16:19], v[172:175], v[204:207], v[16:19]
	v_mfma_f32_16x16x32_bf16 v[4:7], v[164:167], v[212:215], v[4:7]
	v_mfma_f32_16x16x32_bf16 v[0:3], v[172:175], v[212:215], v[0:3]
	s_setprio 1
	s_barrier
	s_add_i32 s53, 0, 0x18000
	s_add_i32 s54, 0, 0x1c000
	v_add_u32_e32 v156, s53, v145
	v_add_u32_e32 v172, s54, v145
	ds_read_b128 v[138:141], v156
	ds_read_b128 v[148:151], v156 offset:1024
	ds_read_b128 v[152:155], v156 offset:2048
	ds_read_b128 v[156:159], v156 offset:3072
	ds_read_b128 v[160:163], v172
	ds_read_b128 v[164:167], v172 offset:1024
	ds_read_b128 v[168:171], v172 offset:2048
	ds_read_b128 v[172:175], v172 offset:3072
	s_add_u32 s44, s44, s12
	s_addc_u32 s45, s45, 0
	s_mov_b32 m0, s17
	v_lshl_add_u64 v[230:231], s[44:45], 0, v[132:133]
	ds_read_b128 v[176:179], v147 offset:32768
	ds_read_b128 v[180:183], v147 offset:33792
	ds_read_b128 v[184:187], v147 offset:34816
	ds_read_b128 v[188:191], v147 offset:35840
	ds_read_b128 v[192:195], v147 offset:36864
	ds_read_b128 v[204:207], v147 offset:37888
	ds_read_b128 v[208:211], v147 offset:38912
	ds_read_b128 v[212:215], v147 offset:39936
	global_load_lds_dwordx4 v[230:231], off
	v_lshl_add_u64 v[230:231], s[44:45], 0, v[130:131]
	s_mov_b32 m0, s26
	s_nop 0
	global_load_lds_dwordx4 v[230:231], off
	s_waitcnt vmcnt(8)
	s_waitcnt lgkmcnt(0)
	s_barrier
	s_setprio 0
	s_waitcnt lgkmcnt(0)
	v_mfma_f32_16x16x32_bf16 v[124:127], v[138:141], v[176:179], v[124:127]
	v_mfma_f32_16x16x32_bf16 v[120:123], v[152:155], v[176:179], v[120:123]
	v_mfma_f32_16x16x32_bf16 v[108:111], v[138:141], v[184:187], v[108:111]
	v_mfma_f32_16x16x32_bf16 v[104:107], v[152:155], v[184:187], v[104:107]
	v_mfma_f32_16x16x32_bf16 v[92:95], v[138:141], v[192:195], v[92:95]
	v_mfma_f32_16x16x32_bf16 v[88:91], v[152:155], v[192:195], v[88:91]
	v_mfma_f32_16x16x32_bf16 v[76:79], v[138:141], v[208:211], v[76:79]
	v_mfma_f32_16x16x32_bf16 v[72:75], v[152:155], v[208:211], v[72:75]
	v_mfma_f32_16x16x32_bf16 v[124:127], v[148:151], v[180:183], v[124:127]
	v_mfma_f32_16x16x32_bf16 v[120:123], v[156:159], v[180:183], v[120:123]
	v_mfma_f32_16x16x32_bf16 v[108:111], v[148:151], v[188:191], v[108:111]
	v_mfma_f32_16x16x32_bf16 v[104:107], v[156:159], v[188:191], v[104:107]
	v_mfma_f32_16x16x32_bf16 v[92:95], v[148:151], v[204:207], v[92:95]
	v_mfma_f32_16x16x32_bf16 v[88:91], v[156:159], v[204:207], v[88:91]
	v_mfma_f32_16x16x32_bf16 v[76:79], v[148:151], v[212:215], v[76:79]
	v_mfma_f32_16x16x32_bf16 v[72:75], v[156:159], v[212:215], v[72:75]
	s_setprio 1
	s_setprio 0
	v_mfma_f32_16x16x32_bf16 v[116:119], v[160:163], v[176:179], v[116:119]
	v_mfma_f32_16x16x32_bf16 v[112:115], v[168:171], v[176:179], v[112:115]
	v_mfma_f32_16x16x32_bf16 v[100:103], v[160:163], v[184:187], v[100:103]
	v_mfma_f32_16x16x32_bf16 v[96:99], v[168:171], v[184:187], v[96:99]
	v_mfma_f32_16x16x32_bf16 v[84:87], v[160:163], v[192:195], v[84:87]
	v_mfma_f32_16x16x32_bf16 v[80:83], v[168:171], v[192:195], v[80:83]
	v_mfma_f32_16x16x32_bf16 v[68:71], v[160:163], v[208:211], v[68:71]
	v_mfma_f32_16x16x32_bf16 v[64:67], v[168:171], v[208:211], v[64:67]
	v_mfma_f32_16x16x32_bf16 v[116:119], v[164:167], v[180:183], v[116:119]
	v_mfma_f32_16x16x32_bf16 v[112:115], v[172:175], v[180:183], v[112:115]
	v_mfma_f32_16x16x32_bf16 v[100:103], v[164:167], v[188:191], v[100:103]
	v_mfma_f32_16x16x32_bf16 v[96:99], v[172:175], v[188:191], v[96:99]
	v_mfma_f32_16x16x32_bf16 v[84:87], v[164:167], v[204:207], v[84:87]
	v_mfma_f32_16x16x32_bf16 v[80:83], v[172:175], v[204:207], v[80:83]
	v_mfma_f32_16x16x32_bf16 v[68:71], v[164:167], v[212:215], v[68:71]
	v_mfma_f32_16x16x32_bf16 v[64:67], v[172:175], v[212:215], v[64:67]
	s_setprio 1
	s_barrier
	s_add_i32 s44, s53, s11
	v_lshl_add_u64 v[142:143], v[142:143], 0, s[88:89]
	s_mov_b32 m0, s44
	ds_read_b128 v[176:179], v147 offset:49152
	ds_read_b128 v[180:183], v147 offset:50176
	ds_read_b128 v[184:187], v147 offset:51200
	ds_read_b128 v[188:191], v147 offset:52224
	ds_read_b128 v[192:195], v147 offset:53248
	ds_read_b128 v[204:207], v147 offset:54272
	ds_read_b128 v[208:211], v147 offset:55296
	ds_read_b128 v[212:215], v147 offset:56320
	global_load_lds_dwordx4 v[142:143], off
	v_lshl_add_u64 v[142:143], v[216:217], 0, s[88:89]
	s_add_i32 m0, s44, 0x2000
	s_add_i32 s44, s54, s11
	global_load_lds_dwordx4 v[142:143], off
	v_lshl_add_u64 v[142:143], v[218:219], 0, s[88:89]
	s_mov_b32 m0, s44
	s_nop 0
	global_load_lds_dwordx4 v[142:143], off
	v_lshl_add_u64 v[142:143], v[220:221], 0, s[88:89]
	s_add_i32 m0, s44, 0x2000
	s_nop 0
	global_load_lds_dwordx4 v[142:143], off
	v_lshl_add_u64 v[142:143], v[226:227], 0, s[88:89]
	s_mov_b32 m0, s29
	s_nop 0
	global_load_lds_dwordx4 v[142:143], off
	v_lshl_add_u64 v[142:143], v[228:229], 0, s[88:89]
	s_mov_b32 m0, s33
	s_nop 0
	global_load_lds_dwordx4 v[142:143], off
	s_waitcnt vmcnt(8)
	s_waitcnt lgkmcnt(0)
	s_barrier
	s_setprio 0
	s_waitcnt lgkmcnt(0)
	v_mfma_f32_16x16x32_bf16 v[60:63], v[138:141], v[176:179], v[60:63]
	v_mfma_f32_16x16x32_bf16 v[56:59], v[152:155], v[176:179], v[56:59]
	v_mfma_f32_16x16x32_bf16 v[44:47], v[138:141], v[184:187], v[44:47]
	v_mfma_f32_16x16x32_bf16 v[40:43], v[152:155], v[184:187], v[40:43]
	v_mfma_f32_16x16x32_bf16 v[28:31], v[138:141], v[192:195], v[28:31]
	v_mfma_f32_16x16x32_bf16 v[24:27], v[152:155], v[192:195], v[24:27]
	v_mfma_f32_16x16x32_bf16 v[12:15], v[138:141], v[208:211], v[12:15]
	v_mfma_f32_16x16x32_bf16 v[8:11], v[152:155], v[208:211], v[8:11]
	v_mfma_f32_16x16x32_bf16 v[60:63], v[148:151], v[180:183], v[60:63]
	v_mfma_f32_16x16x32_bf16 v[56:59], v[156:159], v[180:183], v[56:59]
	v_mfma_f32_16x16x32_bf16 v[44:47], v[148:151], v[188:191], v[44:47]
	v_mfma_f32_16x16x32_bf16 v[40:43], v[156:159], v[188:191], v[40:43]
	v_mfma_f32_16x16x32_bf16 v[28:31], v[148:151], v[204:207], v[28:31]
	v_mfma_f32_16x16x32_bf16 v[24:27], v[156:159], v[204:207], v[24:27]
	v_mfma_f32_16x16x32_bf16 v[12:15], v[148:151], v[212:215], v[12:15]
	v_mfma_f32_16x16x32_bf16 v[8:11], v[156:159], v[212:215], v[8:11]
	s_setprio 1
	s_setprio 0
	v_mfma_f32_16x16x32_bf16 v[52:55], v[160:163], v[176:179], v[52:55]
	v_mfma_f32_16x16x32_bf16 v[48:51], v[168:171], v[176:179], v[48:51]
	v_mfma_f32_16x16x32_bf16 v[36:39], v[160:163], v[184:187], v[36:39]
	v_mfma_f32_16x16x32_bf16 v[32:35], v[168:171], v[184:187], v[32:35]
	v_mfma_f32_16x16x32_bf16 v[20:23], v[160:163], v[192:195], v[20:23]
	v_mfma_f32_16x16x32_bf16 v[16:19], v[168:171], v[192:195], v[16:19]
	v_mfma_f32_16x16x32_bf16 v[4:7], v[160:163], v[208:211], v[4:7]
	v_mfma_f32_16x16x32_bf16 v[0:3], v[168:171], v[208:211], v[0:3]
	v_mfma_f32_16x16x32_bf16 v[52:55], v[164:167], v[180:183], v[52:55]
	v_mfma_f32_16x16x32_bf16 v[48:51], v[172:175], v[180:183], v[48:51]
	v_mfma_f32_16x16x32_bf16 v[36:39], v[164:167], v[188:191], v[36:39]
	v_mfma_f32_16x16x32_bf16 v[32:35], v[172:175], v[188:191], v[32:35]
	v_mfma_f32_16x16x32_bf16 v[20:23], v[164:167], v[204:207], v[20:23]
	v_mfma_f32_16x16x32_bf16 v[16:19], v[172:175], v[204:207], v[16:19]
	v_mfma_f32_16x16x32_bf16 v[4:7], v[164:167], v[212:215], v[4:7]
	v_mfma_f32_16x16x32_bf16 v[0:3], v[172:175], v[212:215], v[0:3]
	s_setprio 1
	s_barrier
	s_add_u32 s34, s34, 0x100
	s_addc_u32 s35, s35, 0
	s_add_u32 s46, s46, 0x100
	s_addc_u32 s47, s47, 0
	s_cmp_ge_u32 s52, s28
	s_mov_b32 s44, s52
	s_cbranch_scc0 .LBB0_855
	s_setprio 0
	s_and_b64 vcc, exec, s[22:23]
	s_cbranch_vccz .LBB0_858
	s_barrier
